# kzz order + peeled first iteration (srcC=0, no zeroing) + per-unit vmcnt(0) of the first SwiGLU GEMM removed
# speedup vs baseline: 1.0249x; 1.0038x over previous
; #define PG8_STAGE(bufoff, gbase, voff) do { _Pragma("unroll") for (int _i = 0; _i < 2; ++_i) \
;         __builtin_amdgcn_global_load_lds((const unsigned*)((const char*)(gbase) + (voff)[_i]), (PG8_LAS unsigned*)(lds + (bufoff) + ldsw + _i * 8192), 16, 0, 0); } while (0)
; #define PG8_LDA(dst, b, h) do { _Pragma("unroll") for (int m = 0; m < 4; ++m) _Pragma("unroll") for (int k = 0; k < 2; ++k) dst[m][k] = *(const PG8_LAS bf16x8*)(lds + PG8_SA(b, h) + aoff + m * 2048 + k * 1024); } while (0)
; #define PG8_LDB(dst, b, h) do { _Pragma("unroll") for (int n = 0; n < 2; ++n) _Pragma("unroll") for (int k = 0; k < 2; ++k) dst[n][k] = *(const PG8_LAS bf16x8*)(lds + PG8_SB(b, h) + boff + n * 2048 + k * 1024); } while (0)
; #define PG8_WAIT_V(n) asm volatile("s_waitcnt vmcnt(" #n ")" ::: "memory")
; #define PG8_WAIT_L(n) asm volatile("s_waitcnt lgkmcnt(" #n ")" ::: "memory")
; template <class Epi, class Sched, bool ALIGN_EPI = false, bool SP2 = false>
; __device__ __forceinline__ void gemm_phase(PG8_LAS unsigned char* lds, const Gemm g, const Sched& S, const Epi& E) {
;     ...
;     for (;;) {
;         const bool has_next = S.next(ui + 1, nxt);
;         const char* nA = has_next ? (const char*)g.A + (size_t)nxt.pm * tstep : cA; const char* nB = has_next ? (const char*)g.Bt + (size_t)nxt.pn * tstep : cB;
;         for (int t = 0; t < nt; t += 2) {
;             const bool last = (t == nt - 2);
;             const char* a1 = cA + (size_t)(t + 1) * kstep;
;             const char* a2 = last ? nA : cA + (size_t)(t + 2) * kstep; const char* b2 = last ? nB : cB + (size_t)(t + 2) * kstep;
;             const char* a3 = a2 + kstep; const char* b3 = b2 + kstep;
;             if (last && has_next) S.a_ready(nxt);
;             if constexpr (Epi::MID) { if (t == nt / 2) E.mid(acc, cur, wr, wc, fr, fq); }
;             if constexpr (SP2) {
;             PG8_LDB(B0, 0, 0); PG8_LDB(B1, 0, 1); PG8_SCHED; PG8_LDA(At, 0, 0); PG8_STAGE(PG8_SA(1, 1), a1 + hstep, voffA);
;             PG8_WAIT_V(8); PG8_WAIT_L(0); PG8_BAR; PG8_MMA(0, 0, At, B0); PG8_MMA(0, 1, At, B1); PG8_BAR; PG8_SCHED;
;             PG8_LDA(At, 0, 1); PG8_STAGE(PG8_SB(0, 0), b2, voffB); PG8_STAGE(PG8_SB(0, 1), b2 + hstep, voffB); PG8_STAGE(PG8_SA(0, 0), a2, voffA);
;             PG8_WAIT_V(8); PG8_WAIT_L(0); PG8_BAR; PG8_MMA(1, 0, At, B0); PG8_MMA(1, 1, At, B1); PG8_BAR; PG8_SCHED;
.LBB0_372:
	s_ashr_i32 s21, s20, 31
	s_lshl_b64 s[22:23], s[20:21], 20
	s_add_u32 s22, s8, s22
	s_addc_u32 s23, s9, s23
	s_and_b64 s[24:25], s[2:3], exec
	s_cselect_b32 s5, s23, s29
	s_cselect_b32 s11, s22, s28
	s_ashr_i32 s19, s18, 31
	s_lshl_b64 s[24:25], s[18:19], 20
	s_add_u32 s24, s35, s24
	s_addc_u32 s25, s36, s25
	s_and_b64 s[30:31], s[2:3], exec
	s_cselect_b32 s19, s25, s27
	s_cselect_b32 s21, s24, s26
	s_add_u32 s53, s26, 0x100
	s_addc_u32 s54, s27, 0
	s_add_u32 s26, s28, 0x80080
	s_addc_u32 s27, s29, 0
	s_mov_b32 s55, -2
	s_add_u32 s28, s26, 0xfff80080
	s_addc_u32 s29, s27, -1
	s_add_i32 s33, 0, 0x10000
	s_cmp_eq_u32 s55, 28
	s_cselect_b32 s31, s5, s29
	s_cselect_b32 s30, s11, s28
	v_add_u32_e32 v161, s33, v155
	s_cselect_b32 s29, s19, s54
	s_cselect_b32 s28, s21, s53
	s_add_i32 s58, 0, 0x14000
	ds_read_b128 v[142:145], v161
	ds_read_b128 v[146:149], v161 offset:1024
	ds_read_b128 v[150:153], v161 offset:2048
	ds_read_b128 v[162:165], v161 offset:3072
	v_add_u32_e32 v161, s58, v155
	ds_read_b128 v[166:169], v161
	ds_read_b128 v[170:173], v161 offset:1024
	ds_read_b128 v[174:177], v161 offset:2048
	ds_read_b128 v[178:181], v161 offset:3072
	v_lshl_add_u64 v[202:203], s[26:27], 0, v[140:141]
	s_add_i32 m0, s41, 0xc000
	ds_read_b128 v[182:185], v160
	ds_read_b128 v[186:189], v160 offset:1024
	ds_read_b128 v[190:193], v160 offset:2048
	ds_read_b128 v[194:197], v160 offset:3072
	ds_read_b128 v[198:201], v160 offset:4096
	ds_read_b128 v[206:209], v160 offset:5120
	ds_read_b128 v[210:213], v160 offset:6144
	ds_read_b128 v[214:217], v160 offset:7168
	global_load_lds_dwordx4 v140, s[26:27]
	v_lshl_add_u64 v[202:203], s[26:27], 0, v[138:139]
	s_add_i32 m0, s41, 0xe000
	s_nop 0
	global_load_lds_dwordx4 v138, s[26:27]
	s_waitcnt vmcnt(8)
	s_waitcnt lgkmcnt(0)
	s_barrier
	s_setprio 1
	s_waitcnt lgkmcnt(0)
	v_mfma_f32_16x16x32_bf16 v[130:133], v[142:145], v[182:185], 0
	v_mfma_f32_16x16x32_bf16 v[130:133], v[146:149], v[186:189], v[130:133]
	v_mfma_f32_16x16x32_bf16 v[126:129], v[162:165], v[186:189], 0
	v_mfma_f32_16x16x32_bf16 v[126:129], v[150:153], v[182:185], v[126:129]
	v_mfma_f32_16x16x32_bf16 v[110:113], v[150:153], v[190:193], 0
	v_mfma_f32_16x16x32_bf16 v[110:113], v[162:165], v[194:197], v[110:113]
	v_mfma_f32_16x16x32_bf16 v[114:117], v[146:149], v[194:197], 0
	v_mfma_f32_16x16x32_bf16 v[114:117], v[142:145], v[190:193], v[114:117]
	v_mfma_f32_16x16x32_bf16 v[98:101], v[142:145], v[198:201], 0
	v_mfma_f32_16x16x32_bf16 v[98:101], v[146:149], v[206:209], v[98:101]
	v_mfma_f32_16x16x32_bf16 v[94:97], v[162:165], v[206:209], 0
	v_mfma_f32_16x16x32_bf16 v[94:97], v[150:153], v[198:201], v[94:97]
	v_mfma_f32_16x16x32_bf16 v[78:81], v[150:153], v[210:213], 0
	v_mfma_f32_16x16x32_bf16 v[78:81], v[162:165], v[214:217], v[78:81]
	v_mfma_f32_16x16x32_bf16 v[82:85], v[146:149], v[214:217], 0
	v_mfma_f32_16x16x32_bf16 v[82:85], v[142:145], v[210:213], v[82:85]
	s_setprio 0
	s_setprio 1
	v_mfma_f32_16x16x32_bf16 v[122:125], v[166:169], v[182:185], 0
	v_mfma_f32_16x16x32_bf16 v[122:125], v[170:173], v[186:189], v[122:125]
	v_mfma_f32_16x16x32_bf16 v[118:121], v[178:181], v[186:189], 0
	v_mfma_f32_16x16x32_bf16 v[118:121], v[174:177], v[182:185], v[118:121]
	v_mfma_f32_16x16x32_bf16 v[102:105], v[174:177], v[190:193], 0
	v_mfma_f32_16x16x32_bf16 v[102:105], v[178:181], v[194:197], v[102:105]
	v_mfma_f32_16x16x32_bf16 v[106:109], v[170:173], v[194:197], 0
	v_mfma_f32_16x16x32_bf16 v[106:109], v[166:169], v[190:193], v[106:109]
	v_mfma_f32_16x16x32_bf16 v[90:93], v[166:169], v[198:201], 0
	v_mfma_f32_16x16x32_bf16 v[90:93], v[170:173], v[206:209], v[90:93]
	v_mfma_f32_16x16x32_bf16 v[86:89], v[178:181], v[206:209], 0
	v_mfma_f32_16x16x32_bf16 v[86:89], v[174:177], v[198:201], v[86:89]
	v_mfma_f32_16x16x32_bf16 v[70:73], v[174:177], v[210:213], 0
	v_mfma_f32_16x16x32_bf16 v[70:73], v[178:181], v[214:217], v[70:73]
	v_mfma_f32_16x16x32_bf16 v[74:77], v[170:173], v[214:217], 0
	v_mfma_f32_16x16x32_bf16 v[74:77], v[166:169], v[210:213], v[74:77]
	s_setprio 0
	s_barrier
	s_add_i32 s33, s33, s39
	v_lshl_add_u64 v[202:203], s[28:29], 0, v[0:1]
	s_mov_b32 m0, s33
	ds_read_b128 v[182:185], v160 offset:16384
	ds_read_b128 v[186:189], v160 offset:17408
	ds_read_b128 v[190:193], v160 offset:18432
	ds_read_b128 v[194:197], v160 offset:19456
	ds_read_b128 v[198:201], v160 offset:20480
	ds_read_b128 v[206:209], v160 offset:21504
	ds_read_b128 v[210:213], v160 offset:22528
	ds_read_b128 v[214:217], v160 offset:23552
	global_load_lds_dwordx4 v0, s[28:29]
	s_add_i32 m0, s33, 0x2000
	s_add_u32 s56, s28, 0x80000
	v_lshl_add_u64 v[218:219], s[28:29], 0, v[14:15]
	s_addc_u32 s57, s29, 0
	s_add_i32 s33, s58, s39
	global_load_lds_dwordx4 v14, s[28:29]
	v_lshl_add_u64 v[220:221], s[56:57], 0, v[0:1]
	s_mov_b32 m0, s33
	v_lshl_add_u64 v[222:223], s[30:31], 0, v[134:135]
	global_load_lds_dwordx4 v0, s[56:57]
	v_lshl_add_u64 v[220:221], s[56:57], 0, v[14:15]
	s_add_i32 m0, s33, 0x2000
	s_nop 0
	global_load_lds_dwordx4 v14, s[56:57]
	v_lshl_add_u64 v[220:221], s[30:31], 0, v[136:137]
	s_mov_b32 m0, s41
	s_nop 0
	global_load_lds_dwordx4 v136, s[30:31]
	s_mov_b32 m0, s42
	s_nop 0
	global_load_lds_dwordx4 v134, s[30:31]
	s_waitcnt vmcnt(8)
	s_waitcnt lgkmcnt(0)
	s_barrier
; #define PG8_STAGE(bufoff, gbase, voff) do { _Pragma("unroll") for (int _i = 0; _i < 2; ++_i) \
;         __builtin_amdgcn_global_load_lds((const unsigned*)((const char*)(gbase) + (voff)[_i]), (PG8_LAS unsigned*)(lds + (bufoff) + ldsw + _i * 8192), 16, 0, 0); } while (0)
; #define PG8_LDA(dst, b, h) do { _Pragma("unroll") for (int m = 0; m < 4; ++m) _Pragma("unroll") for (int k = 0; k < 2; ++k) dst[m][k] = *(const PG8_LAS bf16x8*)(lds + PG8_SA(b, h) + aoff + m * 2048 + k * 1024); } while (0)
; #define PG8_LDB(dst, b, h) do { _Pragma("unroll") for (int n = 0; n < 2; ++n) _Pragma("unroll") for (int k = 0; k < 2; ++k) dst[n][k] = *(const PG8_LAS bf16x8*)(lds + PG8_SB(b, h) + boff + n * 2048 + k * 1024); } while (0)
; #define PG8_MMA(ai, bj, At, Bt) do { __builtin_amdgcn_s_setprio(1); _Pragma("unroll") for (int m = 0; m < 4; ++m) _Pragma("unroll") for (int n = 0; n < 2; ++n) _Pragma("unroll") for (int k = 0; k < 2; ++k) \
;         acc[ai][bj][m][n] = __builtin_amdgcn_mfma_f32_16x16x32_bf16(Bt[n][k], At[m][k], acc[ai][bj][m][n], 0, 0, 0); __builtin_amdgcn_s_setprio(0); } while (0)
; #define PG8_WAIT_V(n) asm volatile("s_waitcnt vmcnt(" #n ")" ::: "memory")
; #define PG8_WAIT_L(n) asm volatile("s_waitcnt lgkmcnt(" #n ")" ::: "memory")
; #define PG8_BAR __builtin_amdgcn_s_barrier()
; #define PG8_SCHED __builtin_amdgcn_sched_barrier(0)
; template <class Epi, class Sched, bool ALIGN_EPI = false, bool SP2 = false>
; __device__ __forceinline__ void gemm_phase(PG8_LAS unsigned char* lds, const Gemm g, const Sched& S, const Epi& E) {
;     ...
;             PG8_WAIT_V(8); PG8_WAIT_L(0); PG8_BAR; PG8_MMA(1, 0, At, B0); PG8_MMA(1, 1, At, B1); PG8_BAR; PG8_SCHED;
;             PG8_LDB(B0, 1, 0); PG8_LDB(B1, 1, 1); PG8_SCHED; PG8_LDA(At, 1, 0); PG8_STAGE(PG8_SA(0, 1), a2 + hstep, voffA);
;             PG8_WAIT_V(8); PG8_WAIT_L(0); PG8_BAR; PG8_MMA(0, 0, At, B0); PG8_MMA(0, 1, At, B1); PG8_BAR; PG8_SCHED;
	s_setprio 1
	s_waitcnt lgkmcnt(0)
	v_mfma_f32_16x16x32_bf16 v[66:69], v[142:145], v[182:185], 0
	v_mfma_f32_16x16x32_bf16 v[66:69], v[146:149], v[186:189], v[66:69]
	v_mfma_f32_16x16x32_bf16 v[62:65], v[162:165], v[186:189], 0
	v_mfma_f32_16x16x32_bf16 v[62:65], v[150:153], v[182:185], v[62:65]
	v_mfma_f32_16x16x32_bf16 v[46:49], v[150:153], v[190:193], 0
	v_mfma_f32_16x16x32_bf16 v[46:49], v[162:165], v[194:197], v[46:49]
	v_mfma_f32_16x16x32_bf16 v[50:53], v[146:149], v[194:197], 0
	v_mfma_f32_16x16x32_bf16 v[50:53], v[142:145], v[190:193], v[50:53]
	v_mfma_f32_16x16x32_bf16 v[34:37], v[142:145], v[198:201], 0
	v_mfma_f32_16x16x32_bf16 v[34:37], v[146:149], v[206:209], v[34:37]
	v_mfma_f32_16x16x32_bf16 v[30:33], v[162:165], v[206:209], 0
	v_mfma_f32_16x16x32_bf16 v[30:33], v[150:153], v[198:201], v[30:33]
	v_mfma_f32_16x16x32_bf16 v[10:13], v[150:153], v[210:213], 0
	v_mfma_f32_16x16x32_bf16 v[10:13], v[162:165], v[214:217], v[10:13]
	v_mfma_f32_16x16x32_bf16 v[18:21], v[146:149], v[214:217], 0
	v_mfma_f32_16x16x32_bf16 v[18:21], v[142:145], v[210:213], v[18:21]
	s_setprio 0
	s_setprio 1
	v_mfma_f32_16x16x32_bf16 v[58:61], v[166:169], v[182:185], 0
	v_mfma_f32_16x16x32_bf16 v[58:61], v[170:173], v[186:189], v[58:61]
	v_mfma_f32_16x16x32_bf16 v[54:57], v[178:181], v[186:189], 0
	v_mfma_f32_16x16x32_bf16 v[54:57], v[174:177], v[182:185], v[54:57]
	v_mfma_f32_16x16x32_bf16 v[38:41], v[174:177], v[190:193], 0
	v_mfma_f32_16x16x32_bf16 v[38:41], v[178:181], v[194:197], v[38:41]
	v_mfma_f32_16x16x32_bf16 v[42:45], v[170:173], v[194:197], 0
	v_mfma_f32_16x16x32_bf16 v[42:45], v[166:169], v[190:193], v[42:45]
	v_mfma_f32_16x16x32_bf16 v[26:29], v[166:169], v[198:201], 0
	v_mfma_f32_16x16x32_bf16 v[26:29], v[170:173], v[206:209], v[26:29]
	v_mfma_f32_16x16x32_bf16 v[22:25], v[178:181], v[206:209], 0
	v_mfma_f32_16x16x32_bf16 v[22:25], v[174:177], v[198:201], v[22:25]
	v_mfma_f32_16x16x32_bf16 v[2:5], v[174:177], v[210:213], 0
	v_mfma_f32_16x16x32_bf16 v[2:5], v[178:181], v[214:217], v[2:5]
	v_mfma_f32_16x16x32_bf16 v[6:9], v[170:173], v[214:217], 0
	v_mfma_f32_16x16x32_bf16 v[6:9], v[166:169], v[210:213], v[6:9]
	s_setprio 0
	s_barrier
	s_add_i32 s33, 0, 0x18000
	v_add_u32_e32 v161, s33, v155
	s_add_i32 s56, 0, 0x1c000
	ds_read_b128 v[142:145], v161
	ds_read_b128 v[146:149], v161 offset:1024
	ds_read_b128 v[150:153], v161 offset:2048
	ds_read_b128 v[162:165], v161 offset:3072
	v_add_u32_e32 v161, s56, v155
	ds_read_b128 v[166:169], v161
	ds_read_b128 v[170:173], v161 offset:1024
	ds_read_b128 v[174:177], v161 offset:2048
	ds_read_b128 v[178:181], v161 offset:3072
	s_add_u32 s30, s30, 0x80000
	s_addc_u32 s31, s31, 0
	s_mov_b32 m0, s43
	v_lshl_add_u64 v[224:225], s[30:31], 0, v[136:137]
	ds_read_b128 v[182:185], v160 offset:32768
	ds_read_b128 v[186:189], v160 offset:33792
	ds_read_b128 v[190:193], v160 offset:34816
	ds_read_b128 v[194:197], v160 offset:35840
	ds_read_b128 v[198:201], v160 offset:36864
	ds_read_b128 v[206:209], v160 offset:37888
	ds_read_b128 v[210:213], v160 offset:38912
	ds_read_b128 v[214:217], v160 offset:39936
	global_load_lds_dwordx4 v136, s[30:31]
	v_lshl_add_u64 v[224:225], s[30:31], 0, v[134:135]
	s_mov_b32 m0, s44
	s_nop 0
	global_load_lds_dwordx4 v134, s[30:31]
	s_waitcnt vmcnt(8)
	s_waitcnt lgkmcnt(0)
	s_barrier
	s_setprio 1
	s_waitcnt lgkmcnt(0)
	v_mfma_f32_16x16x32_bf16 v[130:133], v[142:145], v[182:185], v[130:133]
	v_mfma_f32_16x16x32_bf16 v[130:133], v[146:149], v[186:189], v[130:133]
	v_mfma_f32_16x16x32_bf16 v[126:129], v[162:165], v[186:189], v[126:129]
	v_mfma_f32_16x16x32_bf16 v[126:129], v[150:153], v[182:185], v[126:129]
	v_mfma_f32_16x16x32_bf16 v[110:113], v[150:153], v[190:193], v[110:113]
	v_mfma_f32_16x16x32_bf16 v[110:113], v[162:165], v[194:197], v[110:113]
	v_mfma_f32_16x16x32_bf16 v[114:117], v[146:149], v[194:197], v[114:117]
	v_mfma_f32_16x16x32_bf16 v[114:117], v[142:145], v[190:193], v[114:117]
	v_mfma_f32_16x16x32_bf16 v[98:101], v[142:145], v[198:201], v[98:101]
	v_mfma_f32_16x16x32_bf16 v[98:101], v[146:149], v[206:209], v[98:101]
	v_mfma_f32_16x16x32_bf16 v[94:97], v[162:165], v[206:209], v[94:97]
	v_mfma_f32_16x16x32_bf16 v[94:97], v[150:153], v[198:201], v[94:97]
	v_mfma_f32_16x16x32_bf16 v[78:81], v[150:153], v[210:213], v[78:81]
	v_mfma_f32_16x16x32_bf16 v[78:81], v[162:165], v[214:217], v[78:81]
	v_mfma_f32_16x16x32_bf16 v[82:85], v[146:149], v[214:217], v[82:85]
	v_mfma_f32_16x16x32_bf16 v[82:85], v[142:145], v[210:213], v[82:85]
	s_setprio 0
	s_setprio 1
	v_mfma_f32_16x16x32_bf16 v[122:125], v[166:169], v[182:185], v[122:125]
	v_mfma_f32_16x16x32_bf16 v[122:125], v[170:173], v[186:189], v[122:125]
	v_mfma_f32_16x16x32_bf16 v[118:121], v[178:181], v[186:189], v[118:121]
	v_mfma_f32_16x16x32_bf16 v[118:121], v[174:177], v[182:185], v[118:121]
	v_mfma_f32_16x16x32_bf16 v[102:105], v[174:177], v[190:193], v[102:105]
	v_mfma_f32_16x16x32_bf16 v[102:105], v[178:181], v[194:197], v[102:105]
	v_mfma_f32_16x16x32_bf16 v[106:109], v[170:173], v[194:197], v[106:109]
	v_mfma_f32_16x16x32_bf16 v[106:109], v[166:169], v[190:193], v[106:109]
	v_mfma_f32_16x16x32_bf16 v[90:93], v[166:169], v[198:201], v[90:93]
	v_mfma_f32_16x16x32_bf16 v[90:93], v[170:173], v[206:209], v[90:93]
	v_mfma_f32_16x16x32_bf16 v[86:89], v[178:181], v[206:209], v[86:89]
	v_mfma_f32_16x16x32_bf16 v[86:89], v[174:177], v[198:201], v[86:89]
	v_mfma_f32_16x16x32_bf16 v[70:73], v[174:177], v[210:213], v[70:73]
	v_mfma_f32_16x16x32_bf16 v[70:73], v[178:181], v[214:217], v[70:73]
	v_mfma_f32_16x16x32_bf16 v[74:77], v[170:173], v[214:217], v[74:77]
	v_mfma_f32_16x16x32_bf16 v[74:77], v[166:169], v[210:213], v[74:77]
	s_setprio 0
	s_barrier
; #define PG8_STAGE(bufoff, gbase, voff) do { _Pragma("unroll") for (int _i = 0; _i < 2; ++_i) \
;         __builtin_amdgcn_global_load_lds((const unsigned*)((const char*)(gbase) + (voff)[_i]), (PG8_LAS unsigned*)(lds + (bufoff) + ldsw + _i * 8192), 16, 0, 0); } while (0)
; #define PG8_LDA(dst, b, h) do { _Pragma("unroll") for (int m = 0; m < 4; ++m) _Pragma("unroll") for (int k = 0; k < 2; ++k) dst[m][k] = *(const PG8_LAS bf16x8*)(lds + PG8_SA(b, h) + aoff + m * 2048 + k * 1024); } while (0)
; #define PG8_MMA(ai, bj, At, Bt) do { __builtin_amdgcn_s_setprio(1); _Pragma("unroll") for (int m = 0; m < 4; ++m) _Pragma("unroll") for (int n = 0; n < 2; ++n) _Pragma("unroll") for (int k = 0; k < 2; ++k) \
;         acc[ai][bj][m][n] = __builtin_amdgcn_mfma_f32_16x16x32_bf16(Bt[n][k], At[m][k], acc[ai][bj][m][n], 0, 0, 0); __builtin_amdgcn_s_setprio(0); } while (0)
; #define PG8_WAIT_V(n) asm volatile("s_waitcnt vmcnt(" #n ")" ::: "memory")
; #define PG8_WAIT_L(n) asm volatile("s_waitcnt lgkmcnt(" #n ")" ::: "memory")
; #define PG8_BAR __builtin_amdgcn_s_barrier()
; #define PG8_SCHED __builtin_amdgcn_sched_barrier(0)
; template <class Epi, class Sched, bool ALIGN_EPI = false, bool SP2 = false>
; __device__ __forceinline__ void gemm_phase(PG8_LAS unsigned char* lds, const Gemm g, const Sched& S, const Epi& E) {
;     ...
;         for (int t = 0; t < nt; t += 2) {
;     ...
;             PG8_LDA(At, 1, 1); PG8_STAGE(PG8_SB(1, 0), b3, voffB); PG8_STAGE(PG8_SB(1, 1), b3 + hstep, voffB); PG8_STAGE(PG8_SA(1, 0), a3, voffA);
;             PG8_WAIT_V(8); PG8_WAIT_L(0); PG8_BAR; PG8_MMA(1, 0, At, B0); PG8_MMA(1, 1, At, B1); PG8_BAR; PG8_SCHED;
	s_add_i32 s30, s33, s39
	v_lshl_add_u64 v[202:203], v[202:203], 0, s[92:93]
	s_mov_b32 m0, s30
	ds_read_b128 v[182:185], v160 offset:49152
	ds_read_b128 v[186:189], v160 offset:50176
	ds_read_b128 v[190:193], v160 offset:51200
	ds_read_b128 v[194:197], v160 offset:52224
	ds_read_b128 v[198:201], v160 offset:53248
	ds_read_b128 v[206:209], v160 offset:54272
	ds_read_b128 v[210:213], v160 offset:55296
	ds_read_b128 v[214:217], v160 offset:56320
	global_load_lds_dwordx4 v[202:203], off
	s_add_i32 m0, s30, 0x2000
	s_add_u32 s28, s28, 0x80080
	v_lshl_add_u64 v[202:203], v[218:219], 0, s[92:93]
	s_addc_u32 s29, s29, 0
	s_add_i32 s30, s56, s39
	global_load_lds_dwordx4 v[202:203], off
	v_lshl_add_u64 v[202:203], s[28:29], 0, v[0:1]
	s_mov_b32 m0, s30
	s_nop 0
	global_load_lds_dwordx4 v0, s[28:29]
	v_lshl_add_u64 v[202:203], s[28:29], 0, v[14:15]
	s_add_i32 m0, s30, 0x2000
	s_nop 0
	global_load_lds_dwordx4 v14, s[28:29]
	v_lshl_add_u64 v[202:203], v[220:221], 0, s[92:93]
	s_mov_b32 m0, s46
	s_nop 0
	global_load_lds_dwordx4 v[202:203], off
	v_lshl_add_u64 v[202:203], v[222:223], 0, s[92:93]
	s_mov_b32 m0, s47
	s_nop 0
	global_load_lds_dwordx4 v[202:203], off
	s_waitcnt vmcnt(8)
	s_waitcnt lgkmcnt(0)
	s_barrier
	s_setprio 1
	s_waitcnt lgkmcnt(0)
	v_mfma_f32_16x16x32_bf16 v[66:69], v[142:145], v[182:185], v[66:69]
	v_mfma_f32_16x16x32_bf16 v[66:69], v[146:149], v[186:189], v[66:69]
	v_mfma_f32_16x16x32_bf16 v[62:65], v[162:165], v[186:189], v[62:65]
	v_mfma_f32_16x16x32_bf16 v[62:65], v[150:153], v[182:185], v[62:65]
	v_mfma_f32_16x16x32_bf16 v[46:49], v[150:153], v[190:193], v[46:49]
	v_mfma_f32_16x16x32_bf16 v[46:49], v[162:165], v[194:197], v[46:49]
	v_mfma_f32_16x16x32_bf16 v[50:53], v[146:149], v[194:197], v[50:53]
	v_mfma_f32_16x16x32_bf16 v[50:53], v[142:145], v[190:193], v[50:53]
	v_mfma_f32_16x16x32_bf16 v[34:37], v[142:145], v[198:201], v[34:37]
	v_mfma_f32_16x16x32_bf16 v[34:37], v[146:149], v[206:209], v[34:37]
	v_mfma_f32_16x16x32_bf16 v[30:33], v[162:165], v[206:209], v[30:33]
	v_mfma_f32_16x16x32_bf16 v[30:33], v[150:153], v[198:201], v[30:33]
	v_mfma_f32_16x16x32_bf16 v[10:13], v[150:153], v[210:213], v[10:13]
	v_mfma_f32_16x16x32_bf16 v[10:13], v[162:165], v[214:217], v[10:13]
	v_mfma_f32_16x16x32_bf16 v[18:21], v[146:149], v[214:217], v[18:21]
	v_mfma_f32_16x16x32_bf16 v[18:21], v[142:145], v[210:213], v[18:21]
	s_setprio 0
	s_setprio 1
	v_mfma_f32_16x16x32_bf16 v[58:61], v[166:169], v[182:185], v[58:61]
	v_mfma_f32_16x16x32_bf16 v[58:61], v[170:173], v[186:189], v[58:61]
	v_mfma_f32_16x16x32_bf16 v[54:57], v[178:181], v[186:189], v[54:57]
	v_mfma_f32_16x16x32_bf16 v[54:57], v[174:177], v[182:185], v[54:57]
	v_mfma_f32_16x16x32_bf16 v[38:41], v[174:177], v[190:193], v[38:41]
	v_mfma_f32_16x16x32_bf16 v[38:41], v[178:181], v[194:197], v[38:41]
	v_mfma_f32_16x16x32_bf16 v[42:45], v[170:173], v[194:197], v[42:45]
	v_mfma_f32_16x16x32_bf16 v[42:45], v[166:169], v[190:193], v[42:45]
	v_mfma_f32_16x16x32_bf16 v[26:29], v[166:169], v[198:201], v[26:29]
	v_mfma_f32_16x16x32_bf16 v[26:29], v[170:173], v[206:209], v[26:29]
	v_mfma_f32_16x16x32_bf16 v[22:25], v[178:181], v[206:209], v[22:25]
	v_mfma_f32_16x16x32_bf16 v[22:25], v[174:177], v[198:201], v[22:25]
	v_mfma_f32_16x16x32_bf16 v[2:5], v[174:177], v[210:213], v[2:5]
	v_mfma_f32_16x16x32_bf16 v[2:5], v[178:181], v[214:217], v[2:5]
	v_mfma_f32_16x16x32_bf16 v[6:9], v[170:173], v[214:217], v[6:9]
	v_mfma_f32_16x16x32_bf16 v[6:9], v[166:169], v[210:213], v[6:9]
	s_setprio 0
	s_barrier
	s_add_i32 s55, s55, 2
	s_add_u32 s53, s53, 0x100
	s_addc_u32 s54, s54, 0
	s_add_u32 s26, s26, 0x100
	s_addc_u32 s27, s27, 0
	s_cmp_gt_u32 s55, 29
